# A->B group arrive/wait (permutation-safe placement check) combined with skipping the launch-time cooperative grid sync
# speedup vs baseline: 1.0094x; 1.0094x over previous
.LBB0_5:
	s_or_b64 exec, exec, s[4:5]
	v_lshrrev_b32_e32 v2, 20, v0
	v_lshrrev_b32_e32 v0, 10, v0
	v_or_b32_e32 v0, v0, v2
	s_movk_i32 s4, 0x3ff
	v_and_or_b32 v0, v0, s4, v1
	v_cmp_eq_u32_e32 vcc, 0, v0
	s_barrier
	s_and_saveexec_b64 s[4:5], vcc
	s_branch .LBB0_15
	buffer_wbl2 sc1
	s_waitcnt vmcnt(0)
	s_load_dwordx2 s[6:7], s[6:7], 0x58
	v_mov_b32_e32 v3, 0
	s_mov_b64 s[8:9], exec
	v_mbcnt_lo_u32_b32 v2, s8, 0
	v_mbcnt_hi_u32_b32 v2, s9, v2
	s_waitcnt lgkmcnt(0)
	global_load_dword v0, v3, s[6:7] offset:40
	v_cmp_eq_u32_e32 vcc, 0, v2
	s_and_saveexec_b64 s[10:11], vcc
	s_cbranch_execz .LBB0_8
	s_bcnt1_i32_b64 s8, s[8:9]
	v_mov_b32_e32 v4, s8
	global_atomic_add v4, v3, v4, s[6:7] offset:32 sc0
